# GU K-loops: in load sections 1 and 3 the A-fragment LDS reads are issued first so the scalar pointer/flag work runs in their latency shadow (pure reorder)
# speedup vs baseline: 1.0174x; 1.0174x over previous
; #define PG8_STAGE(bufoff, gbase, voff) do { _Pragma("unroll") for (int _i = 0; _i < 2; ++_i) \
;         __builtin_amdgcn_global_load_lds((const unsigned*)((const char*)(gbase) + (voff)[_i]), (LAS unsigned*)(lds + (bufoff) + ldsw + _i * 8192), 16, 0, 0); } while (0)
; #define PG8_LDA(dst, b, h) do { _Pragma("unroll") for (int m = 0; m < 4; ++m) _Pragma("unroll") for (int k = 0; k < 2; ++k) dst[m][k] = *(const LAS bf16x8*)(lds + PG8_SA(b, h) + aoff + m * 2048 + k * 1024); } while (0)
; #define PG8_LDB(dst, b, h) do { _Pragma("unroll") for (int n = 0; n < 2; ++n) _Pragma("unroll") for (int k = 0; k < 2; ++k) dst[n][k] = *(const LAS bf16x8*)(lds + PG8_SB(b, h) + boff + n * 2048 + k * 1024); } while (0)
; #define PG8_MMA(ai, bj, At, Bt) do { __builtin_amdgcn_s_setprio(1); _Pragma("unroll") for (int m = 0; m < 4; ++m) _Pragma("unroll") for (int n = 0; n < 2; ++n) _Pragma("unroll") for (int k = 0; k < 2; ++k) \
;         acc[ai][bj][m][n] = __builtin_amdgcn_mfma_f32_16x16x32_bf16(Bt[n][k], At[m][k], acc[ai][bj][m][n], 0, 0, 0); __builtin_amdgcn_s_setprio(0); } while (0)
; #define PG8_WAIT_V(n) asm volatile("s_waitcnt vmcnt(" #n ")" ::: "memory")
; #define PG8_WAIT_L(n) asm volatile("s_waitcnt lgkmcnt(" #n ")" ::: "memory")
; #define PG8_BAR __builtin_amdgcn_s_barrier()
; #define PG8_SCHED __builtin_amdgcn_sched_barrier(0)
; template <class Epi>
; __device__ __forceinline__ void gemm_phase(LAS unsigned char* lds, const int tid, const Gemm g, const StaticOrder& S, const Epi& E) {
;     ...
;             PG8_LDB(B0, 0, 0); PG8_LDB(B1, 0, 1); PG8_SCHED; PG8_LDA(At, 0, 0); PG8_STAGE(PG8_SA(1, 1), a1 + hstepA, voffA);
;             PG8_WAIT_V(8); PG8_WAIT_L(0); PG8_BAR; PG8_MMA(0, 0, At, B0); PG8_MMA(0, 1, At, B1); PG8_BAR; PG8_SCHED;
;             PG8_LDA(At, 0, 1); PG8_STAGE(PG8_SB(0, 0), b2, voffB); PG8_STAGE(PG8_SB(0, 1), b2 + hstepB, voffB); PG8_STAGE(PG8_SA(0, 0), a2, voffA);
;             PG8_WAIT_V(8); PG8_WAIT_L(0); PG8_BAR; PG8_MMA(1, 0, At, B0); PG8_MMA(1, 1, At, B1); PG8_BAR; PG8_SCHED;
.LBB0_263:
	ds_read_b128 v[188:191], v153
	ds_read_b128 v[192:195], v153 offset:1024
	ds_read_b128 v[196:199], v153 offset:2048
	ds_read_b128 v[200:203], v153 offset:3072
	ds_read_b128 v[204:207], v153 offset:4096
	ds_read_b128 v[208:211], v153 offset:5120
	ds_read_b128 v[212:215], v153 offset:6144
	ds_read_b128 v[216:219], v153 offset:7168
	v_add_u32_e32 v184, s52, v151
	ds_read_b128 v[172:175], v184
	ds_read_b128 v[176:179], v184 offset:1024
	ds_read_b128 v[180:183], v184 offset:2048
	ds_read_b128 v[184:187], v184 offset:3072
	s_add_i32 s58, s58, 2
	s_add_u32 s30, s26, 0xfffc0080
	s_addc_u32 s31, s27, -1
	s_and_b64 s[28:29], s[28:29], exec
	s_cselect_b32 s31, s17, s31
	s_cselect_b32 s30, s19, s30
	s_cselect_b32 s29, s55, s57
	s_cselect_b32 s28, s56, s25
	s_add_i32 m0, s41, 0xc000
	v_lshl_add_u64 v[220:221], s[26:27], 0, v[140:141]
	global_load_lds_dwordx4 v[220:221], off
	v_lshl_add_u64 v[220:221], s[26:27], 0, v[138:139]
	s_add_i32 m0, s41, 0xe000
	s_nop 0
	global_load_lds_dwordx4 v[220:221], off
	s_waitcnt vmcnt(6)
	s_waitcnt lgkmcnt(0)
	s_barrier
	s_setprio 1
	v_mfma_f32_16x16x32_bf16 v[120:123], v[156:159], v[188:191], v[120:123]
	v_mfma_f32_16x16x32_bf16 v[116:119], v[164:167], v[188:191], v[116:119]
	v_mfma_f32_16x16x32_bf16 v[108:111], v[156:159], v[196:199], v[108:111]
	v_mfma_f32_16x16x32_bf16 v[100:103], v[164:167], v[196:199], v[100:103]
	v_mfma_f32_16x16x32_bf16 v[92:95], v[156:159], v[204:207], v[92:95]
	v_mfma_f32_16x16x32_bf16 v[84:87], v[164:167], v[204:207], v[84:87]
	v_mfma_f32_16x16x32_bf16 v[76:79], v[156:159], v[212:215], v[76:79]
	v_mfma_f32_16x16x32_bf16 v[68:71], v[164:167], v[212:215], v[68:71]
	v_mfma_f32_16x16x32_bf16 v[120:123], v[160:163], v[192:195], v[120:123]
	v_mfma_f32_16x16x32_bf16 v[116:119], v[168:171], v[192:195], v[116:119]
	v_mfma_f32_16x16x32_bf16 v[108:111], v[160:163], v[200:203], v[108:111]
	v_mfma_f32_16x16x32_bf16 v[100:103], v[168:171], v[200:203], v[100:103]
	v_mfma_f32_16x16x32_bf16 v[92:95], v[160:163], v[208:211], v[92:95]
	v_mfma_f32_16x16x32_bf16 v[84:87], v[168:171], v[208:211], v[84:87]
	v_mfma_f32_16x16x32_bf16 v[76:79], v[160:163], v[216:219], v[76:79]
	v_mfma_f32_16x16x32_bf16 v[68:71], v[168:171], v[216:219], v[68:71]
	v_mfma_f32_16x16x32_bf16 v[124:127], v[172:175], v[188:191], v[124:127]
	v_mfma_f32_16x16x32_bf16 v[112:115], v[180:183], v[188:191], v[112:115]
	v_mfma_f32_16x16x32_bf16 v[104:107], v[172:175], v[196:199], v[104:107]
	v_mfma_f32_16x16x32_bf16 v[96:99], v[180:183], v[196:199], v[96:99]
	v_mfma_f32_16x16x32_bf16 v[88:91], v[172:175], v[204:207], v[88:91]
	v_mfma_f32_16x16x32_bf16 v[80:83], v[180:183], v[204:207], v[80:83]
	v_mfma_f32_16x16x32_bf16 v[72:75], v[172:175], v[212:215], v[72:75]
	v_mfma_f32_16x16x32_bf16 v[64:67], v[180:183], v[212:215], v[64:67]
	v_mfma_f32_16x16x32_bf16 v[124:127], v[176:179], v[192:195], v[124:127]
	v_mfma_f32_16x16x32_bf16 v[112:115], v[184:187], v[192:195], v[112:115]
	v_mfma_f32_16x16x32_bf16 v[104:107], v[176:179], v[200:203], v[104:107]
	v_mfma_f32_16x16x32_bf16 v[96:99], v[184:187], v[200:203], v[96:99]
	v_mfma_f32_16x16x32_bf16 v[88:91], v[176:179], v[208:211], v[88:91]
	v_mfma_f32_16x16x32_bf16 v[80:83], v[184:187], v[208:211], v[80:83]
	v_mfma_f32_16x16x32_bf16 v[72:75], v[176:179], v[216:219], v[72:75]
	v_mfma_f32_16x16x32_bf16 v[64:67], v[184:187], v[216:219], v[64:67]
	s_setprio 0
	s_barrier
	s_add_i32 s59, s51, s38
	v_lshl_add_u64 v[220:221], s[28:29], 0, v[132:133]
	s_mov_b32 m0, s59
	ds_read_b128 v[188:191], v153 offset:16384
	ds_read_b128 v[192:195], v153 offset:17408
	ds_read_b128 v[196:199], v153 offset:18432
	ds_read_b128 v[200:203], v153 offset:19456
	ds_read_b128 v[204:207], v153 offset:20480
	ds_read_b128 v[208:211], v153 offset:21504
	ds_read_b128 v[212:215], v153 offset:22528
	ds_read_b128 v[216:219], v153 offset:23552
	global_load_lds_dwordx4 v[220:221], off
	s_add_i32 m0, s59, 0x2000
	s_add_u32 s60, s28, 0x40000
	v_lshl_add_u64 v[222:223], s[28:29], 0, v[128:129]
	s_addc_u32 s61, s29, 0
	s_add_i32 s59, s52, s38
	global_load_lds_dwordx4 v[222:223], off
	v_lshl_add_u64 v[224:225], s[60:61], 0, v[132:133]
	s_mov_b32 m0, s59
	v_lshl_add_u64 v[226:227], s[30:31], 0, v[130:131]
	global_load_lds_dwordx4 v[224:225], off
	v_lshl_add_u64 v[224:225], s[60:61], 0, v[128:129]
	s_add_i32 m0, s59, 0x2000
	s_nop 0
	global_load_lds_dwordx4 v[224:225], off
	v_lshl_add_u64 v[224:225], s[30:31], 0, v[134:135]
	s_mov_b32 m0, s41
	s_nop 0
	global_load_lds_dwordx4 v[224:225], off
	s_mov_b32 m0, s42
	s_nop 0
	global_load_lds_dwordx4 v[226:227], off
	s_waitcnt vmcnt(8)
	s_waitcnt lgkmcnt(0)
	s_barrier
; #define PG8_STAGE(bufoff, gbase, voff) do { _Pragma("unroll") for (int _i = 0; _i < 2; ++_i) \
;         __builtin_amdgcn_global_load_lds((const unsigned*)((const char*)(gbase) + (voff)[_i]), (LAS unsigned*)(lds + (bufoff) + ldsw + _i * 8192), 16, 0, 0); } while (0)
; #define PG8_LDA(dst, b, h) do { _Pragma("unroll") for (int m = 0; m < 4; ++m) _Pragma("unroll") for (int k = 0; k < 2; ++k) dst[m][k] = *(const LAS bf16x8*)(lds + PG8_SA(b, h) + aoff + m * 2048 + k * 1024); } while (0)
; #define PG8_LDB(dst, b, h) do { _Pragma("unroll") for (int n = 0; n < 2; ++n) _Pragma("unroll") for (int k = 0; k < 2; ++k) dst[n][k] = *(const LAS bf16x8*)(lds + PG8_SB(b, h) + boff + n * 2048 + k * 1024); } while (0)
; #define PG8_MMA(ai, bj, At, Bt) do { __builtin_amdgcn_s_setprio(1); _Pragma("unroll") for (int m = 0; m < 4; ++m) _Pragma("unroll") for (int n = 0; n < 2; ++n) _Pragma("unroll") for (int k = 0; k < 2; ++k) \
;         acc[ai][bj][m][n] = __builtin_amdgcn_mfma_f32_16x16x32_bf16(Bt[n][k], At[m][k], acc[ai][bj][m][n], 0, 0, 0); __builtin_amdgcn_s_setprio(0); } while (0)
; #define PG8_WAIT_V(n) asm volatile("s_waitcnt vmcnt(" #n ")" ::: "memory")
; #define PG8_WAIT_L(n) asm volatile("s_waitcnt lgkmcnt(" #n ")" ::: "memory")
; #define PG8_BAR __builtin_amdgcn_s_barrier()
; #define PG8_SCHED __builtin_amdgcn_sched_barrier(0)
; template <class Epi>
; __device__ __forceinline__ void gemm_phase(LAS unsigned char* lds, const int tid, const Gemm g, const StaticOrder& S, const Epi& E) {
;     ...
;             PG8_WAIT_V(8); PG8_WAIT_L(0); PG8_BAR; PG8_MMA(1, 0, At, B0); PG8_MMA(1, 1, At, B1); PG8_BAR; PG8_SCHED;
;             PG8_LDB(B0, 1, 0); PG8_LDB(B1, 1, 1); PG8_SCHED; PG8_LDA(At, 1, 0); PG8_STAGE(PG8_SA(0, 1), a2 + hstepA, voffA);
;             PG8_WAIT_V(8); PG8_WAIT_L(0); PG8_BAR; PG8_MMA(0, 0, At, B0); PG8_MMA(0, 1, At, B1); PG8_BAR; PG8_SCHED;
	s_setprio 1
	v_mfma_f32_16x16x32_bf16 v[60:63], v[156:159], v[188:191], v[60:63]
	v_mfma_f32_16x16x32_bf16 v[52:55], v[164:167], v[188:191], v[52:55]
	v_mfma_f32_16x16x32_bf16 v[44:47], v[156:159], v[196:199], v[44:47]
	v_mfma_f32_16x16x32_bf16 v[36:39], v[164:167], v[196:199], v[36:39]
	v_mfma_f32_16x16x32_bf16 v[28:31], v[156:159], v[204:207], v[28:31]
	v_mfma_f32_16x16x32_bf16 v[20:23], v[164:167], v[204:207], v[20:23]
	v_mfma_f32_16x16x32_bf16 v[12:15], v[156:159], v[212:215], v[12:15]
	v_mfma_f32_16x16x32_bf16 v[4:7], v[164:167], v[212:215], v[4:7]
	v_mfma_f32_16x16x32_bf16 v[60:63], v[160:163], v[192:195], v[60:63]
	v_mfma_f32_16x16x32_bf16 v[52:55], v[168:171], v[192:195], v[52:55]
	v_mfma_f32_16x16x32_bf16 v[44:47], v[160:163], v[200:203], v[44:47]
	v_mfma_f32_16x16x32_bf16 v[36:39], v[168:171], v[200:203], v[36:39]
	v_mfma_f32_16x16x32_bf16 v[28:31], v[160:163], v[208:211], v[28:31]
	v_mfma_f32_16x16x32_bf16 v[20:23], v[168:171], v[208:211], v[20:23]
	v_mfma_f32_16x16x32_bf16 v[12:15], v[160:163], v[216:219], v[12:15]
	v_mfma_f32_16x16x32_bf16 v[4:7], v[168:171], v[216:219], v[4:7]
	v_mfma_f32_16x16x32_bf16 v[56:59], v[172:175], v[188:191], v[56:59]
	v_add_u32_e32 v168, 0x18000, v151
	v_mfma_f32_16x16x32_bf16 v[48:51], v[180:183], v[188:191], v[48:51]
	v_mfma_f32_16x16x32_bf16 v[40:43], v[172:175], v[196:199], v[40:43]
	ds_read_b128 v[156:159], v168
	v_mfma_f32_16x16x32_bf16 v[32:35], v[180:183], v[196:199], v[32:35]
	v_mfma_f32_16x16x32_bf16 v[24:27], v[172:175], v[204:207], v[24:27]
	v_mfma_f32_16x16x32_bf16 v[16:19], v[180:183], v[204:207], v[16:19]
	ds_read_b128 v[160:163], v168 offset:1024
	v_mfma_f32_16x16x32_bf16 v[8:11], v[172:175], v[212:215], v[8:11]
	v_mfma_f32_16x16x32_bf16 v[0:3], v[180:183], v[212:215], v[0:3]
	v_mfma_f32_16x16x32_bf16 v[56:59], v[176:179], v[192:195], v[56:59]
	ds_read_b128 v[164:167], v168 offset:2048
	v_mfma_f32_16x16x32_bf16 v[48:51], v[184:187], v[192:195], v[48:51]
	v_mfma_f32_16x16x32_bf16 v[40:43], v[176:179], v[200:203], v[40:43]
	v_mfma_f32_16x16x32_bf16 v[32:35], v[184:187], v[200:203], v[32:35]
	ds_read_b128 v[168:171], v168 offset:3072
	v_mfma_f32_16x16x32_bf16 v[24:27], v[176:179], v[208:211], v[24:27]
	v_mfma_f32_16x16x32_bf16 v[16:19], v[184:187], v[208:211], v[16:19]
	v_mfma_f32_16x16x32_bf16 v[8:11], v[176:179], v[216:219], v[8:11]
	v_mfma_f32_16x16x32_bf16 v[0:3], v[184:187], v[216:219], v[0:3]
	s_setprio 0
	s_barrier
	s_add_i32 s59, 0, 0x18000
	s_add_i32 s60, 0, 0x1c000
	ds_read_b128 v[188:191], v153 offset:32768
	ds_read_b128 v[192:195], v153 offset:33792
	ds_read_b128 v[196:199], v153 offset:34816
	ds_read_b128 v[200:203], v153 offset:35840
	ds_read_b128 v[204:207], v153 offset:36864
	ds_read_b128 v[208:211], v153 offset:37888
	ds_read_b128 v[212:215], v153 offset:38912
	ds_read_b128 v[216:219], v153 offset:39936
	v_add_u32_e32 v184, s60, v151
	ds_read_b128 v[172:175], v184
	ds_read_b128 v[176:179], v184 offset:1024
	ds_read_b128 v[180:183], v184 offset:2048
	ds_read_b128 v[184:187], v184 offset:3072
	s_add_u32 s30, s30, 0x40000
	s_addc_u32 s31, s31, 0
	s_mov_b32 m0, s43
	v_lshl_add_u64 v[228:229], s[30:31], 0, v[134:135]
	global_load_lds_dwordx4 v[228:229], off
	v_lshl_add_u64 v[228:229], s[30:31], 0, v[130:131]
	s_mov_b32 m0, s44
	s_nop 0
	global_load_lds_dwordx4 v[228:229], off
	s_waitcnt vmcnt(6)
	s_waitcnt lgkmcnt(0)
	s_barrier
	s_setprio 1
	v_mfma_f32_16x16x32_bf16 v[120:123], v[156:159], v[188:191], v[120:123]
	v_mfma_f32_16x16x32_bf16 v[116:119], v[164:167], v[188:191], v[116:119]
	v_mfma_f32_16x16x32_bf16 v[108:111], v[156:159], v[196:199], v[108:111]
	v_mfma_f32_16x16x32_bf16 v[100:103], v[164:167], v[196:199], v[100:103]
	v_mfma_f32_16x16x32_bf16 v[92:95], v[156:159], v[204:207], v[92:95]
	v_mfma_f32_16x16x32_bf16 v[84:87], v[164:167], v[204:207], v[84:87]
	v_mfma_f32_16x16x32_bf16 v[76:79], v[156:159], v[212:215], v[76:79]
	v_mfma_f32_16x16x32_bf16 v[68:71], v[164:167], v[212:215], v[68:71]
	v_mfma_f32_16x16x32_bf16 v[120:123], v[160:163], v[192:195], v[120:123]
	v_mfma_f32_16x16x32_bf16 v[116:119], v[168:171], v[192:195], v[116:119]
	v_mfma_f32_16x16x32_bf16 v[108:111], v[160:163], v[200:203], v[108:111]
	v_mfma_f32_16x16x32_bf16 v[100:103], v[168:171], v[200:203], v[100:103]
	v_mfma_f32_16x16x32_bf16 v[92:95], v[160:163], v[208:211], v[92:95]
	v_mfma_f32_16x16x32_bf16 v[84:87], v[168:171], v[208:211], v[84:87]
	v_mfma_f32_16x16x32_bf16 v[76:79], v[160:163], v[216:219], v[76:79]
	v_mfma_f32_16x16x32_bf16 v[68:71], v[168:171], v[216:219], v[68:71]
	v_mfma_f32_16x16x32_bf16 v[124:127], v[172:175], v[188:191], v[124:127]
	v_mfma_f32_16x16x32_bf16 v[112:115], v[180:183], v[188:191], v[112:115]
	v_mfma_f32_16x16x32_bf16 v[104:107], v[172:175], v[196:199], v[104:107]
	v_mfma_f32_16x16x32_bf16 v[96:99], v[180:183], v[196:199], v[96:99]
	v_mfma_f32_16x16x32_bf16 v[88:91], v[172:175], v[204:207], v[88:91]
	v_mfma_f32_16x16x32_bf16 v[80:83], v[180:183], v[204:207], v[80:83]
	v_mfma_f32_16x16x32_bf16 v[72:75], v[172:175], v[212:215], v[72:75]
	v_mfma_f32_16x16x32_bf16 v[64:67], v[180:183], v[212:215], v[64:67]
	v_mfma_f32_16x16x32_bf16 v[124:127], v[176:179], v[192:195], v[124:127]
	v_mfma_f32_16x16x32_bf16 v[112:115], v[184:187], v[192:195], v[112:115]
	v_mfma_f32_16x16x32_bf16 v[104:107], v[176:179], v[200:203], v[104:107]
	v_mfma_f32_16x16x32_bf16 v[96:99], v[184:187], v[200:203], v[96:99]
	v_mfma_f32_16x16x32_bf16 v[88:91], v[176:179], v[208:211], v[88:91]
	v_mfma_f32_16x16x32_bf16 v[80:83], v[184:187], v[208:211], v[80:83]
	v_mfma_f32_16x16x32_bf16 v[72:75], v[176:179], v[216:219], v[72:75]
	v_mfma_f32_16x16x32_bf16 v[64:67], v[184:187], v[216:219], v[64:67]
	s_setprio 0
	s_barrier
; #define PG8_STAGE(bufoff, gbase, voff) do { _Pragma("unroll") for (int _i = 0; _i < 2; ++_i) \
;         __builtin_amdgcn_global_load_lds((const unsigned*)((const char*)(gbase) + (voff)[_i]), (LAS unsigned*)(lds + (bufoff) + ldsw + _i * 8192), 16, 0, 0); } while (0)
; #define PG8_LDA(dst, b, h) do { _Pragma("unroll") for (int m = 0; m < 4; ++m) _Pragma("unroll") for (int k = 0; k < 2; ++k) dst[m][k] = *(const LAS bf16x8*)(lds + PG8_SA(b, h) + aoff + m * 2048 + k * 1024); } while (0)
; #define PG8_MMA(ai, bj, At, Bt) do { __builtin_amdgcn_s_setprio(1); _Pragma("unroll") for (int m = 0; m < 4; ++m) _Pragma("unroll") for (int n = 0; n < 2; ++n) _Pragma("unroll") for (int k = 0; k < 2; ++k) \
;         acc[ai][bj][m][n] = __builtin_amdgcn_mfma_f32_16x16x32_bf16(Bt[n][k], At[m][k], acc[ai][bj][m][n], 0, 0, 0); __builtin_amdgcn_s_setprio(0); } while (0)
; #define PG8_WAIT_V(n) asm volatile("s_waitcnt vmcnt(" #n ")" ::: "memory")
; #define PG8_WAIT_L(n) asm volatile("s_waitcnt lgkmcnt(" #n ")" ::: "memory")
; #define PG8_BAR __builtin_amdgcn_s_barrier()
; #define PG8_SCHED __builtin_amdgcn_sched_barrier(0)
; template <class Epi>
; __device__ __forceinline__ void gemm_phase(LAS unsigned char* lds, const int tid, const Gemm g, const StaticOrder& S, const Epi& E) {
;     ...
;             PG8_LDA(At, 1, 1); PG8_STAGE(PG8_SB(1, 0), b3, voffB); PG8_STAGE(PG8_SB(1, 1), b3 + hstepB, voffB); PG8_STAGE(PG8_SA(1, 0), a3, voffA);
;             PG8_WAIT_V(8); PG8_WAIT_L(0); PG8_BAR; PG8_MMA(1, 0, At, B0); PG8_MMA(1, 1, At, B1); PG8_BAR; PG8_SCHED;
	s_add_i32 s30, s59, s38
	v_lshl_add_u64 v[220:221], v[220:221], 0, s[12:13]
	s_mov_b32 m0, s30
	ds_read_b128 v[188:191], v153 offset:49152
	ds_read_b128 v[192:195], v153 offset:50176
	ds_read_b128 v[196:199], v153 offset:51200
	ds_read_b128 v[200:203], v153 offset:52224
	ds_read_b128 v[204:207], v153 offset:53248
	ds_read_b128 v[208:211], v153 offset:54272
	ds_read_b128 v[212:215], v153 offset:55296
	ds_read_b128 v[216:219], v153 offset:56320
	global_load_lds_dwordx4 v[220:221], off
	s_add_i32 m0, s30, 0x2000
	s_add_u32 s28, s28, 0x40080
	v_lshl_add_u64 v[220:221], v[222:223], 0, s[12:13]
	s_addc_u32 s29, s29, 0
	s_add_i32 s30, s60, s38
	global_load_lds_dwordx4 v[220:221], off
	v_lshl_add_u64 v[220:221], s[28:29], 0, v[132:133]
	s_mov_b32 m0, s30
	s_nop 0
	global_load_lds_dwordx4 v[220:221], off
	v_lshl_add_u64 v[220:221], s[28:29], 0, v[128:129]
	s_add_i32 m0, s30, 0x2000
	s_nop 0
	global_load_lds_dwordx4 v[220:221], off
	v_lshl_add_u64 v[220:221], v[224:225], 0, s[12:13]
	s_mov_b32 m0, s47
	s_nop 0
	global_load_lds_dwordx4 v[220:221], off
	v_lshl_add_u64 v[220:221], v[226:227], 0, s[12:13]
	s_mov_b32 m0, s48
	s_nop 0
	global_load_lds_dwordx4 v[220:221], off
	s_add_u32 s25, s25, 0x100
	s_addc_u32 s57, s57, 0
	s_add_u32 s26, s26, 0x100
	s_addc_u32 s27, s27, 0
	s_cmp_eq_u32 s49, s58
	s_cselect_b64 s[28:29], -1, 0
	s_waitcnt vmcnt(8)
	s_waitcnt lgkmcnt(0)
	s_barrier
	s_setprio 1
	v_mfma_f32_16x16x32_bf16 v[60:63], v[156:159], v[188:191], v[60:63]
	v_mfma_f32_16x16x32_bf16 v[52:55], v[164:167], v[188:191], v[52:55]
	v_mfma_f32_16x16x32_bf16 v[44:47], v[156:159], v[196:199], v[44:47]
	v_mfma_f32_16x16x32_bf16 v[36:39], v[164:167], v[196:199], v[36:39]
	v_mfma_f32_16x16x32_bf16 v[28:31], v[156:159], v[204:207], v[28:31]
	v_mfma_f32_16x16x32_bf16 v[20:23], v[164:167], v[204:207], v[20:23]
	v_mfma_f32_16x16x32_bf16 v[12:15], v[156:159], v[212:215], v[12:15]
	v_mfma_f32_16x16x32_bf16 v[4:7], v[164:167], v[212:215], v[4:7]
	v_mfma_f32_16x16x32_bf16 v[60:63], v[160:163], v[192:195], v[60:63]
	v_mfma_f32_16x16x32_bf16 v[52:55], v[168:171], v[192:195], v[52:55]
	v_mfma_f32_16x16x32_bf16 v[44:47], v[160:163], v[200:203], v[44:47]
	v_mfma_f32_16x16x32_bf16 v[36:39], v[168:171], v[200:203], v[36:39]
	v_mfma_f32_16x16x32_bf16 v[28:31], v[160:163], v[208:211], v[28:31]
	v_mfma_f32_16x16x32_bf16 v[20:23], v[168:171], v[208:211], v[20:23]
	v_mfma_f32_16x16x32_bf16 v[12:15], v[160:163], v[216:219], v[12:15]
	v_mfma_f32_16x16x32_bf16 v[4:7], v[168:171], v[216:219], v[4:7]
	v_mfma_f32_16x16x32_bf16 v[56:59], v[172:175], v[188:191], v[56:59]
	v_add_u32_e32 v168, s51, v151
	v_mfma_f32_16x16x32_bf16 v[48:51], v[180:183], v[188:191], v[48:51]
	v_mfma_f32_16x16x32_bf16 v[40:43], v[172:175], v[196:199], v[40:43]
	ds_read_b128 v[156:159], v168
	v_mfma_f32_16x16x32_bf16 v[32:35], v[180:183], v[196:199], v[32:35]
	v_mfma_f32_16x16x32_bf16 v[24:27], v[172:175], v[204:207], v[24:27]
	v_mfma_f32_16x16x32_bf16 v[16:19], v[180:183], v[204:207], v[16:19]
	ds_read_b128 v[160:163], v168 offset:1024
	v_mfma_f32_16x16x32_bf16 v[8:11], v[172:175], v[212:215], v[8:11]
	v_mfma_f32_16x16x32_bf16 v[0:3], v[180:183], v[212:215], v[0:3]
	v_mfma_f32_16x16x32_bf16 v[56:59], v[176:179], v[192:195], v[56:59]
	ds_read_b128 v[164:167], v168 offset:2048
	v_mfma_f32_16x16x32_bf16 v[48:51], v[184:187], v[192:195], v[48:51]
	v_mfma_f32_16x16x32_bf16 v[40:43], v[176:179], v[200:203], v[40:43]
	v_mfma_f32_16x16x32_bf16 v[32:35], v[184:187], v[200:203], v[32:35]
	ds_read_b128 v[168:171], v168 offset:3072
	v_mfma_f32_16x16x32_bf16 v[24:27], v[176:179], v[208:211], v[24:27]
	v_mfma_f32_16x16x32_bf16 v[16:19], v[184:187], v[208:211], v[16:19]
	v_mfma_f32_16x16x32_bf16 v[8:11], v[176:179], v[216:219], v[8:11]
	v_mfma_f32_16x16x32_bf16 v[0:3], v[184:187], v[216:219], v[0:3]
	s_setprio 0
	s_barrier
	s_cmp_ge_i32 s58, s46
	s_cbranch_scc1 .LBB0_266
	s_cmp_lg_u32 s49, s58
	s_cbranch_scc1 .LBB0_263
	s_branch .Lrs_1
